# v3: SwiGLU epilogue rewritten as 8 independent interleaved chains with packed f32 mul/add (same per-element ops)
# speedup vs baseline: 1.0035x; 1.0035x over previous
.LBB0_422:
	s_andn2_b64 vcc, exec, s[38:39]
	v_lshl_or_b32 v148, s28, 7, v144
	v_lshl_add_u32 v146, s29, 8, v142
	v_ashrrev_i32_e32 v149, 31, v148
	v_mov_b64_e32 v[140:141], s[42:43]
	v_mov_b32_e32 v168, 0xbfb8aa3b
	v_mov_b32_e32 v169, 0xbfb8aa3b
	v_lshlrev_b64 v[150:151], 1, v[148:149]
	v_pk_mul_f32 v[156:157], v[126:127], v[168:169]
	v_pk_mul_f32 v[158:159], v[128:129], v[168:169]
	v_pk_mul_f32 v[160:161], v[118:119], v[168:169]
	v_pk_mul_f32 v[162:163], v[120:121], v[168:169]
	v_mad_i64_i32 v[154:155], s[0:1], v146, s75, v[140:141]
	v_exp_f32_e32 v156, v156
	v_exp_f32_e32 v157, v157
	v_exp_f32_e32 v158, v158
	v_exp_f32_e32 v159, v159
	v_exp_f32_e32 v160, v160
	v_exp_f32_e32 v161, v161
	v_exp_f32_e32 v162, v162
	v_exp_f32_e32 v163, v163
	v_lshl_add_u64 v[154:155], v[154:155], 0, v[150:151]
	v_pk_add_f32 v[156:157], v[156:157], 1.0 op_sel_hi:[1,0]
	v_pk_add_f32 v[158:159], v[158:159], 1.0 op_sel_hi:[1,0]
	v_pk_add_f32 v[160:161], v[160:161], 1.0 op_sel_hi:[1,0]
	v_pk_add_f32 v[162:163], v[162:163], 1.0 op_sel_hi:[1,0]
	v_rcp_f32_e32 v156, v156
	v_rcp_f32_e32 v157, v157
	v_rcp_f32_e32 v158, v158
	v_rcp_f32_e32 v159, v159
	v_rcp_f32_e32 v160, v160
	v_rcp_f32_e32 v161, v161
	v_rcp_f32_e32 v162, v162
	v_rcp_f32_e32 v163, v163
	s_nop 0
	v_pk_mul_f32 v[156:157], v[126:127], v[156:157]
	v_pk_mul_f32 v[158:159], v[128:129], v[158:159]
	v_pk_mul_f32 v[160:161], v[118:119], v[160:161]
	v_pk_mul_f32 v[162:163], v[120:121], v[162:163]
	v_pk_mul_f32 v[156:157], v[156:157], v[122:123]
	v_pk_mul_f32 v[158:159], v[158:159], v[124:125]
	v_pk_mul_f32 v[160:161], v[160:161], v[114:115]
	v_pk_mul_f32 v[162:163], v[162:163], v[116:117]
	v_cvt_pk_bf16_f32 v164, v156, v157
	v_cvt_pk_bf16_f32 v165, v158, v159
	v_cvt_pk_bf16_f32 v166, v160, v161
	v_cvt_pk_bf16_f32 v167, v162, v163
	global_store_dwordx4 v[154:155], v[164:167], off
	v_pk_mul_f32 v[156:157], v[110:111], v[168:169]
	v_pk_mul_f32 v[158:159], v[112:113], v[168:169]
	v_pk_mul_f32 v[160:161], v[102:103], v[168:169]
	v_pk_mul_f32 v[162:163], v[104:105], v[168:169]
	v_or_b32_e32 v152, 16, v146
	v_mad_i64_i32 v[154:155], s[0:1], v152, s75, v[140:141]
	v_exp_f32_e32 v156, v156
	v_exp_f32_e32 v157, v157
	v_exp_f32_e32 v158, v158
	v_exp_f32_e32 v159, v159
	v_exp_f32_e32 v160, v160
	v_exp_f32_e32 v161, v161
	v_exp_f32_e32 v162, v162
	v_exp_f32_e32 v163, v163
	v_lshl_add_u64 v[154:155], v[154:155], 0, v[150:151]
	v_pk_add_f32 v[156:157], v[156:157], 1.0 op_sel_hi:[1,0]
	v_pk_add_f32 v[158:159], v[158:159], 1.0 op_sel_hi:[1,0]
	v_pk_add_f32 v[160:161], v[160:161], 1.0 op_sel_hi:[1,0]
	v_pk_add_f32 v[162:163], v[162:163], 1.0 op_sel_hi:[1,0]
	v_rcp_f32_e32 v156, v156
	v_rcp_f32_e32 v157, v157
	v_rcp_f32_e32 v158, v158
	v_rcp_f32_e32 v159, v159
	v_rcp_f32_e32 v160, v160
	v_rcp_f32_e32 v161, v161
	v_rcp_f32_e32 v162, v162
	v_rcp_f32_e32 v163, v163
	s_nop 0
	v_pk_mul_f32 v[156:157], v[110:111], v[156:157]
	v_pk_mul_f32 v[158:159], v[112:113], v[158:159]
	v_pk_mul_f32 v[160:161], v[102:103], v[160:161]
	v_pk_mul_f32 v[162:163], v[104:105], v[162:163]
	v_pk_mul_f32 v[156:157], v[156:157], v[106:107]
	v_pk_mul_f32 v[158:159], v[158:159], v[108:109]
	v_pk_mul_f32 v[160:161], v[160:161], v[98:99]
	v_pk_mul_f32 v[162:163], v[162:163], v[100:101]
	v_cvt_pk_bf16_f32 v164, v156, v157
	v_cvt_pk_bf16_f32 v165, v158, v159
	v_cvt_pk_bf16_f32 v166, v160, v161
	v_cvt_pk_bf16_f32 v167, v162, v163
	global_store_dwordx4 v[154:155], v[164:167], off
	v_pk_mul_f32 v[156:157], v[94:95], v[168:169]
	v_pk_mul_f32 v[158:159], v[96:97], v[168:169]
	v_pk_mul_f32 v[160:161], v[86:87], v[168:169]
	v_pk_mul_f32 v[162:163], v[88:89], v[168:169]
	v_or_b32_e32 v152, 32, v146
	v_mad_i64_i32 v[154:155], s[0:1], v152, s75, v[140:141]
	v_exp_f32_e32 v156, v156
	v_exp_f32_e32 v157, v157
	v_exp_f32_e32 v158, v158
	v_exp_f32_e32 v159, v159
	v_exp_f32_e32 v160, v160
	v_exp_f32_e32 v161, v161
	v_exp_f32_e32 v162, v162
	v_exp_f32_e32 v163, v163
	v_lshl_add_u64 v[154:155], v[154:155], 0, v[150:151]
	v_pk_add_f32 v[156:157], v[156:157], 1.0 op_sel_hi:[1,0]
	v_pk_add_f32 v[158:159], v[158:159], 1.0 op_sel_hi:[1,0]
	v_pk_add_f32 v[160:161], v[160:161], 1.0 op_sel_hi:[1,0]
	v_pk_add_f32 v[162:163], v[162:163], 1.0 op_sel_hi:[1,0]
	v_rcp_f32_e32 v156, v156
	v_rcp_f32_e32 v157, v157
	v_rcp_f32_e32 v158, v158
	v_rcp_f32_e32 v159, v159
	v_rcp_f32_e32 v160, v160
	v_rcp_f32_e32 v161, v161
	v_rcp_f32_e32 v162, v162
	v_rcp_f32_e32 v163, v163
	s_nop 0
	v_pk_mul_f32 v[156:157], v[94:95], v[156:157]
	v_pk_mul_f32 v[158:159], v[96:97], v[158:159]
	v_pk_mul_f32 v[160:161], v[86:87], v[160:161]
	v_pk_mul_f32 v[162:163], v[88:89], v[162:163]
	v_pk_mul_f32 v[156:157], v[156:157], v[90:91]
	v_pk_mul_f32 v[158:159], v[158:159], v[92:93]
	v_pk_mul_f32 v[160:161], v[160:161], v[82:83]
	v_pk_mul_f32 v[162:163], v[162:163], v[84:85]
	v_cvt_pk_bf16_f32 v164, v156, v157
	v_cvt_pk_bf16_f32 v165, v158, v159
	v_cvt_pk_bf16_f32 v166, v160, v161
	v_cvt_pk_bf16_f32 v167, v162, v163
	global_store_dwordx4 v[154:155], v[164:167], off
	v_pk_mul_f32 v[156:157], v[78:79], v[168:169]
	v_pk_mul_f32 v[158:159], v[80:81], v[168:169]
	v_pk_mul_f32 v[160:161], v[70:71], v[168:169]
	v_pk_mul_f32 v[162:163], v[72:73], v[168:169]
	v_or_b32_e32 v152, 48, v146
	v_mad_i64_i32 v[154:155], s[0:1], v152, s75, v[140:141]
	v_exp_f32_e32 v156, v156
	v_exp_f32_e32 v157, v157
	v_exp_f32_e32 v158, v158
	v_exp_f32_e32 v159, v159
	v_exp_f32_e32 v160, v160
	v_exp_f32_e32 v161, v161
	v_exp_f32_e32 v162, v162
	v_exp_f32_e32 v163, v163
	v_lshl_add_u64 v[154:155], v[154:155], 0, v[150:151]
	v_pk_add_f32 v[156:157], v[156:157], 1.0 op_sel_hi:[1,0]
	v_pk_add_f32 v[158:159], v[158:159], 1.0 op_sel_hi:[1,0]
	v_pk_add_f32 v[160:161], v[160:161], 1.0 op_sel_hi:[1,0]
	v_pk_add_f32 v[162:163], v[162:163], 1.0 op_sel_hi:[1,0]
	v_rcp_f32_e32 v156, v156
	v_rcp_f32_e32 v157, v157
	v_rcp_f32_e32 v158, v158
	v_rcp_f32_e32 v159, v159
	v_rcp_f32_e32 v160, v160
	v_rcp_f32_e32 v161, v161
	v_rcp_f32_e32 v162, v162
	v_rcp_f32_e32 v163, v163
	s_nop 0
	v_pk_mul_f32 v[156:157], v[78:79], v[156:157]
	v_pk_mul_f32 v[158:159], v[80:81], v[158:159]
	v_pk_mul_f32 v[160:161], v[70:71], v[160:161]
	v_pk_mul_f32 v[162:163], v[72:73], v[162:163]
	v_pk_mul_f32 v[156:157], v[156:157], v[74:75]
	v_pk_mul_f32 v[158:159], v[158:159], v[76:77]
	v_pk_mul_f32 v[160:161], v[160:161], v[66:67]
	v_pk_mul_f32 v[162:163], v[162:163], v[68:69]
	v_cvt_pk_bf16_f32 v164, v156, v157
	v_cvt_pk_bf16_f32 v165, v158, v159
	v_cvt_pk_bf16_f32 v166, v160, v161
	v_cvt_pk_bf16_f32 v167, v162, v163
	global_store_dwordx4 v[154:155], v[164:167], off
	v_pk_mul_f32 v[156:157], v[62:63], v[168:169]
	v_pk_mul_f32 v[158:159], v[64:65], v[168:169]
	v_pk_mul_f32 v[160:161], v[54:55], v[168:169]
	v_pk_mul_f32 v[162:163], v[56:57], v[168:169]
	v_add_u32_e32 v152, 0x80, v146
	v_mad_i64_i32 v[154:155], s[0:1], v152, s75, v[140:141]
	v_exp_f32_e32 v156, v156
	v_exp_f32_e32 v157, v157
	v_exp_f32_e32 v158, v158
	v_exp_f32_e32 v159, v159
	v_exp_f32_e32 v160, v160
	v_exp_f32_e32 v161, v161
	v_exp_f32_e32 v162, v162
	v_exp_f32_e32 v163, v163
	v_lshl_add_u64 v[154:155], v[154:155], 0, v[150:151]
	v_pk_add_f32 v[156:157], v[156:157], 1.0 op_sel_hi:[1,0]
	v_pk_add_f32 v[158:159], v[158:159], 1.0 op_sel_hi:[1,0]
	v_pk_add_f32 v[160:161], v[160:161], 1.0 op_sel_hi:[1,0]
	v_pk_add_f32 v[162:163], v[162:163], 1.0 op_sel_hi:[1,0]
	v_rcp_f32_e32 v156, v156
	v_rcp_f32_e32 v157, v157
	v_rcp_f32_e32 v158, v158
	v_rcp_f32_e32 v159, v159
	v_rcp_f32_e32 v160, v160
	v_rcp_f32_e32 v161, v161
	v_rcp_f32_e32 v162, v162
	v_rcp_f32_e32 v163, v163
	s_nop 0
	v_pk_mul_f32 v[156:157], v[62:63], v[156:157]
	v_pk_mul_f32 v[158:159], v[64:65], v[158:159]
	v_pk_mul_f32 v[160:161], v[54:55], v[160:161]
	v_pk_mul_f32 v[162:163], v[56:57], v[162:163]
	v_pk_mul_f32 v[156:157], v[156:157], v[58:59]
	v_pk_mul_f32 v[158:159], v[158:159], v[60:61]
	v_pk_mul_f32 v[160:161], v[160:161], v[50:51]
	v_pk_mul_f32 v[162:163], v[162:163], v[52:53]
	v_cvt_pk_bf16_f32 v164, v156, v157
	v_cvt_pk_bf16_f32 v165, v158, v159
	v_cvt_pk_bf16_f32 v166, v160, v161
	v_cvt_pk_bf16_f32 v167, v162, v163
	global_store_dwordx4 v[154:155], v[164:167], off
	v_pk_mul_f32 v[156:157], v[46:47], v[168:169]
	v_pk_mul_f32 v[158:159], v[48:49], v[168:169]
	v_pk_mul_f32 v[160:161], v[38:39], v[168:169]
	v_pk_mul_f32 v[162:163], v[40:41], v[168:169]
	v_add_u32_e32 v152, 0x90, v146
	v_mad_i64_i32 v[154:155], s[0:1], v152, s75, v[140:141]
	v_exp_f32_e32 v156, v156
	v_exp_f32_e32 v157, v157
	v_exp_f32_e32 v158, v158
	v_exp_f32_e32 v159, v159
	v_exp_f32_e32 v160, v160
	v_exp_f32_e32 v161, v161
	v_exp_f32_e32 v162, v162
	v_exp_f32_e32 v163, v163
	v_lshl_add_u64 v[154:155], v[154:155], 0, v[150:151]
	v_pk_add_f32 v[156:157], v[156:157], 1.0 op_sel_hi:[1,0]
	v_pk_add_f32 v[158:159], v[158:159], 1.0 op_sel_hi:[1,0]
	v_pk_add_f32 v[160:161], v[160:161], 1.0 op_sel_hi:[1,0]
	v_pk_add_f32 v[162:163], v[162:163], 1.0 op_sel_hi:[1,0]
	v_rcp_f32_e32 v156, v156
	v_rcp_f32_e32 v157, v157
	v_rcp_f32_e32 v158, v158
	v_rcp_f32_e32 v159, v159
	v_rcp_f32_e32 v160, v160
	v_rcp_f32_e32 v161, v161
	v_rcp_f32_e32 v162, v162
	v_rcp_f32_e32 v163, v163
	s_nop 0
	v_pk_mul_f32 v[156:157], v[46:47], v[156:157]
	v_pk_mul_f32 v[158:159], v[48:49], v[158:159]
	v_pk_mul_f32 v[160:161], v[38:39], v[160:161]
	v_pk_mul_f32 v[162:163], v[40:41], v[162:163]
	v_pk_mul_f32 v[156:157], v[156:157], v[42:43]
	v_pk_mul_f32 v[158:159], v[158:159], v[44:45]
	v_pk_mul_f32 v[160:161], v[160:161], v[34:35]
	v_pk_mul_f32 v[162:163], v[162:163], v[36:37]
	v_cvt_pk_bf16_f32 v164, v156, v157
	v_cvt_pk_bf16_f32 v165, v158, v159
	v_cvt_pk_bf16_f32 v166, v160, v161
	v_cvt_pk_bf16_f32 v167, v162, v163
	global_store_dwordx4 v[154:155], v[164:167], off
	v_pk_mul_f32 v[156:157], v[30:31], v[168:169]
	v_pk_mul_f32 v[158:159], v[32:33], v[168:169]
	v_pk_mul_f32 v[160:161], v[22:23], v[168:169]
	v_pk_mul_f32 v[162:163], v[24:25], v[168:169]
	v_add_u32_e32 v152, 0xa0, v146
	v_mad_i64_i32 v[154:155], s[0:1], v152, s75, v[140:141]
	v_exp_f32_e32 v156, v156
	v_exp_f32_e32 v157, v157
	v_exp_f32_e32 v158, v158
	v_exp_f32_e32 v159, v159
	v_exp_f32_e32 v160, v160
	v_exp_f32_e32 v161, v161
	v_exp_f32_e32 v162, v162
	v_exp_f32_e32 v163, v163
	v_lshl_add_u64 v[154:155], v[154:155], 0, v[150:151]
	v_pk_add_f32 v[156:157], v[156:157], 1.0 op_sel_hi:[1,0]
	v_pk_add_f32 v[158:159], v[158:159], 1.0 op_sel_hi:[1,0]
	v_pk_add_f32 v[160:161], v[160:161], 1.0 op_sel_hi:[1,0]
	v_pk_add_f32 v[162:163], v[162:163], 1.0 op_sel_hi:[1,0]
	v_rcp_f32_e32 v156, v156
	v_rcp_f32_e32 v157, v157
	v_rcp_f32_e32 v158, v158
	v_rcp_f32_e32 v159, v159
	v_rcp_f32_e32 v160, v160
	v_rcp_f32_e32 v161, v161
	v_rcp_f32_e32 v162, v162
	v_rcp_f32_e32 v163, v163
	s_nop 0
	v_pk_mul_f32 v[156:157], v[30:31], v[156:157]
	v_pk_mul_f32 v[158:159], v[32:33], v[158:159]
	v_pk_mul_f32 v[160:161], v[22:23], v[160:161]
	v_pk_mul_f32 v[162:163], v[24:25], v[162:163]
	v_pk_mul_f32 v[156:157], v[156:157], v[26:27]
	v_pk_mul_f32 v[158:159], v[158:159], v[28:29]
	v_pk_mul_f32 v[160:161], v[160:161], v[18:19]
	v_pk_mul_f32 v[162:163], v[162:163], v[20:21]
	v_cvt_pk_bf16_f32 v164, v156, v157
	v_cvt_pk_bf16_f32 v165, v158, v159
	v_cvt_pk_bf16_f32 v166, v160, v161
	v_cvt_pk_bf16_f32 v167, v162, v163
	global_store_dwordx4 v[154:155], v[164:167], off
	v_pk_mul_f32 v[156:157], v[14:15], v[168:169]
	v_pk_mul_f32 v[158:159], v[16:17], v[168:169]
	v_pk_mul_f32 v[160:161], v[6:7], v[168:169]
	v_pk_mul_f32 v[162:163], v[8:9], v[168:169]
	v_add_u32_e32 v152, 0xb0, v146
	v_mad_i64_i32 v[154:155], s[0:1], v152, s75, v[140:141]
	v_exp_f32_e32 v156, v156
	v_exp_f32_e32 v157, v157
	v_exp_f32_e32 v158, v158
	v_exp_f32_e32 v159, v159
	v_exp_f32_e32 v160, v160
	v_exp_f32_e32 v161, v161
	v_exp_f32_e32 v162, v162
	v_exp_f32_e32 v163, v163
	v_lshl_add_u64 v[154:155], v[154:155], 0, v[150:151]
	v_pk_add_f32 v[156:157], v[156:157], 1.0 op_sel_hi:[1,0]
	v_pk_add_f32 v[158:159], v[158:159], 1.0 op_sel_hi:[1,0]
	v_pk_add_f32 v[160:161], v[160:161], 1.0 op_sel_hi:[1,0]
	v_pk_add_f32 v[162:163], v[162:163], 1.0 op_sel_hi:[1,0]
	v_rcp_f32_e32 v156, v156
	v_rcp_f32_e32 v157, v157
	v_rcp_f32_e32 v158, v158
	v_rcp_f32_e32 v159, v159
	v_rcp_f32_e32 v160, v160
	v_rcp_f32_e32 v161, v161
	v_rcp_f32_e32 v162, v162
	v_rcp_f32_e32 v163, v163
	s_mov_b64 s[0:1], -1
	v_pk_mul_f32 v[156:157], v[14:15], v[156:157]
	v_pk_mul_f32 v[158:159], v[16:17], v[158:159]
	v_pk_mul_f32 v[160:161], v[6:7], v[160:161]
	v_pk_mul_f32 v[162:163], v[8:9], v[162:163]
	v_pk_mul_f32 v[156:157], v[156:157], v[10:11]
	v_pk_mul_f32 v[158:159], v[158:159], v[12:13]
	v_pk_mul_f32 v[160:161], v[160:161], v[2:3]
	v_pk_mul_f32 v[162:163], v[162:163], v[4:5]
	v_cvt_pk_bf16_f32 v164, v156, v157
	v_cvt_pk_bf16_f32 v165, v158, v159
	v_cvt_pk_bf16_f32 v166, v160, v161
	v_cvt_pk_bf16_f32 v167, v162, v163
	global_store_dwordx4 v[154:155], v[164:167], off
	s_cbranch_vccnz .LBB0_415
	s_andn2_b64 vcc, exec, s[40:41]
	s_cbranch_vccnz .LBB0_414
	s_barrier
	s_branch .LBB0_414
